# GEMM K-loops (up, down, in-proj main, in-proj transposed): first two counted vmcnt waits skipped in the first iteration of non-first units so epilogue stores drain under compute
# speedup vs baseline: 1.0077x; 1.0077x over previous
.LBB0_106:
	s_add_u32 s0, s42, 0xfffc0080
	s_addc_u32 s1, s43, -1
	s_add_i32 s46, 0, 0x10000
	s_cmp_eq_u32 s35, 12
	s_cselect_b32 s5, s6, s1
	s_cselect_b32 s4, s7, s0
	v_add_u32_e32 v0, s46, v223
	s_cselect_b32 s1, s27, s34
	s_cselect_b32 s0, s28, s29
	s_add_i32 s50, 0, 0x14000
	ds_read_b128 v[130:133], v0
	ds_read_b128 v[134:137], v0 offset:1024
	ds_read_b128 v[150:153], v0 offset:2048
	ds_read_b128 v[154:157], v0 offset:3072
	v_add_u32_e32 v0, s50, v223
	ds_read_b128 v[170:173], v0
	ds_read_b128 v[174:177], v0 offset:1024
	ds_read_b128 v[178:181], v0 offset:2048
	ds_read_b128 v[182:185], v0 offset:3072
	v_lshl_add_u64 v[158:159], s[42:43], 0, v[146:147]
	s_add_i32 m0, s13, 0xc000
	ds_read_b128 v[186:189], v225
	ds_read_b128 v[190:193], v225 offset:1024
	ds_read_b128 v[194:197], v225 offset:2048
	ds_read_b128 v[198:201], v225 offset:3072
	ds_read_b128 v[202:205], v225 offset:4096
	ds_read_b128 v[226:229], v225 offset:5120
	ds_read_b128 v[230:233], v225 offset:6144
	ds_read_b128 v[234:237], v225 offset:7168
	global_load_lds_dwordx4 v[158:159], off
	v_lshl_add_u64 v[158:159], s[42:43], 0, v[148:149]
	s_add_i32 m0, s13, 0xe000
	s_nop 0
	global_load_lds_dwordx4 v[158:159], off
	s_cmp_lg_u32 s35, -2
	s_cbranch_scc1 .Lwt__106_0
	s_cmp_lt_u32 s26, 2
	s_cbranch_scc0 .Lws__106_0
.Lwt__106_0:
	s_waitcnt vmcnt(8)
.Lws__106_0:
	s_waitcnt lgkmcnt(0)
	s_barrier
	s_setprio 1
	s_waitcnt lgkmcnt(0)
	v_mfma_f32_16x16x32_bf16 v[126:129], v[130:133], v[186:189], v[126:129]
	v_mfma_f32_16x16x32_bf16 v[62:65], v[150:153], v[186:189], v[62:65]
	v_mfma_f32_16x16x32_bf16 v[110:113], v[130:133], v[194:197], v[110:113]
	v_mfma_f32_16x16x32_bf16 v[46:49], v[150:153], v[194:197], v[46:49]
	v_mfma_f32_16x16x32_bf16 v[106:109], v[130:133], v[202:205], v[106:109]
	v_mfma_f32_16x16x32_bf16 v[42:45], v[150:153], v[202:205], v[42:45]
	v_mfma_f32_16x16x32_bf16 v[118:121], v[130:133], v[230:233], v[118:121]
	v_mfma_f32_16x16x32_bf16 v[54:57], v[150:153], v[230:233], v[54:57]
	v_mfma_f32_16x16x32_bf16 v[126:129], v[134:137], v[190:193], v[126:129]
	v_mfma_f32_16x16x32_bf16 v[62:65], v[154:157], v[190:193], v[62:65]
	v_mfma_f32_16x16x32_bf16 v[110:113], v[134:137], v[198:201], v[110:113]
	v_mfma_f32_16x16x32_bf16 v[46:49], v[154:157], v[198:201], v[46:49]
	v_mfma_f32_16x16x32_bf16 v[106:109], v[134:137], v[226:229], v[106:109]
	v_mfma_f32_16x16x32_bf16 v[42:45], v[154:157], v[226:229], v[42:45]
	v_mfma_f32_16x16x32_bf16 v[118:121], v[134:137], v[234:237], v[118:121]
	v_mfma_f32_16x16x32_bf16 v[54:57], v[154:157], v[234:237], v[54:57]
	s_setprio 0
	s_setprio 1
	v_mfma_f32_16x16x32_bf16 v[122:125], v[170:173], v[186:189], v[122:125]
	v_mfma_f32_16x16x32_bf16 v[58:61], v[178:181], v[186:189], v[58:61]
	v_mfma_f32_16x16x32_bf16 v[102:105], v[170:173], v[194:197], v[102:105]
	v_mfma_f32_16x16x32_bf16 v[38:41], v[178:181], v[194:197], v[38:41]
	v_mfma_f32_16x16x32_bf16 v[98:101], v[170:173], v[202:205], v[98:101]
	v_mfma_f32_16x16x32_bf16 v[34:37], v[178:181], v[202:205], v[34:37]
	v_mfma_f32_16x16x32_bf16 v[114:117], v[170:173], v[230:233], v[114:117]
	v_mfma_f32_16x16x32_bf16 v[50:53], v[178:181], v[230:233], v[50:53]
	v_mfma_f32_16x16x32_bf16 v[122:125], v[174:177], v[190:193], v[122:125]
	v_mfma_f32_16x16x32_bf16 v[58:61], v[182:185], v[190:193], v[58:61]
	v_mfma_f32_16x16x32_bf16 v[102:105], v[174:177], v[198:201], v[102:105]
	v_mfma_f32_16x16x32_bf16 v[38:41], v[182:185], v[198:201], v[38:41]
	v_mfma_f32_16x16x32_bf16 v[98:101], v[174:177], v[226:229], v[98:101]
	v_mfma_f32_16x16x32_bf16 v[34:37], v[182:185], v[226:229], v[34:37]
	v_mfma_f32_16x16x32_bf16 v[114:117], v[174:177], v[234:237], v[114:117]
	v_mfma_f32_16x16x32_bf16 v[50:53], v[182:185], v[234:237], v[50:53]
	s_setprio 0
	s_barrier
	s_add_i32 s46, s46, s12
	v_lshl_add_u64 v[158:159], s[0:1], 0, v[140:141]
	s_mov_b32 m0, s46
	ds_read_b128 v[186:189], v225 offset:16384
	ds_read_b128 v[190:193], v225 offset:17408
	ds_read_b128 v[194:197], v225 offset:18432
	ds_read_b128 v[198:201], v225 offset:19456
	ds_read_b128 v[202:205], v225 offset:20480
	ds_read_b128 v[226:229], v225 offset:21504
	ds_read_b128 v[230:233], v225 offset:22528
	ds_read_b128 v[234:237], v225 offset:23552
	global_load_lds_dwordx4 v[158:159], off
	s_add_i32 m0, s46, 0x2000
	s_add_u32 s46, s0, 0x40000
	v_lshl_add_u64 v[206:207], s[0:1], 0, v[144:145]
	s_addc_u32 s47, s1, 0
	s_add_i32 s50, s50, s12
	global_load_lds_dwordx4 v[206:207], off
	v_lshl_add_u64 v[238:239], s[46:47], 0, v[140:141]
	s_mov_b32 m0, s50
	v_lshl_add_u64 v[240:241], s[4:5], 0, v[142:143]
	global_load_lds_dwordx4 v[238:239], off
	v_lshl_add_u64 v[238:239], s[46:47], 0, v[144:145]
	s_add_i32 m0, s50, 0x2000
	s_nop 0
	global_load_lds_dwordx4 v[238:239], off
	v_lshl_add_u64 v[238:239], s[4:5], 0, v[138:139]
	s_mov_b32 m0, s13
	s_nop 0
	global_load_lds_dwordx4 v[238:239], off
	s_mov_b32 m0, s14
	s_nop 0
	global_load_lds_dwordx4 v[240:241], off
	s_cmp_lg_u32 s35, -2
	s_cbranch_scc1 .Lwt__106_1
	s_cmp_lt_u32 s26, 2
	s_cbranch_scc0 .Lws__106_1

.Lws__106_1:
	s_waitcnt lgkmcnt(0)
	s_barrier
	s_setprio 1
	s_waitcnt lgkmcnt(0)
	v_mfma_f32_16x16x32_bf16 v[94:97], v[130:133], v[186:189], v[94:97]
	v_mfma_f32_16x16x32_bf16 v[30:33], v[150:153], v[186:189], v[30:33]
	v_mfma_f32_16x16x32_bf16 v[78:81], v[130:133], v[194:197], v[78:81]
	v_mfma_f32_16x16x32_bf16 v[18:21], v[150:153], v[194:197], v[18:21]
	v_mfma_f32_16x16x32_bf16 v[74:77], v[130:133], v[202:205], v[74:77]
	v_mfma_f32_16x16x32_bf16 v[10:13], v[150:153], v[202:205], v[10:13]
	v_mfma_f32_16x16x32_bf16 v[86:89], v[130:133], v[230:233], v[86:89]
	v_mfma_f32_16x16x32_bf16 v[22:25], v[150:153], v[230:233], v[22:25]
	v_mfma_f32_16x16x32_bf16 v[94:97], v[134:137], v[190:193], v[94:97]
	v_mfma_f32_16x16x32_bf16 v[30:33], v[154:157], v[190:193], v[30:33]
	v_mfma_f32_16x16x32_bf16 v[78:81], v[134:137], v[198:201], v[78:81]
	v_mfma_f32_16x16x32_bf16 v[18:21], v[154:157], v[198:201], v[18:21]
	v_mfma_f32_16x16x32_bf16 v[74:77], v[134:137], v[226:229], v[74:77]
	v_mfma_f32_16x16x32_bf16 v[10:13], v[154:157], v[226:229], v[10:13]
	v_mfma_f32_16x16x32_bf16 v[86:89], v[134:137], v[234:237], v[86:89]
	v_mfma_f32_16x16x32_bf16 v[22:25], v[154:157], v[234:237], v[22:25]
	s_setprio 0
	s_setprio 1
	v_mfma_f32_16x16x32_bf16 v[90:93], v[170:173], v[186:189], v[90:93]
	v_mfma_f32_16x16x32_bf16 v[26:29], v[178:181], v[186:189], v[26:29]
	v_mfma_f32_16x16x32_bf16 v[70:73], v[170:173], v[194:197], v[70:73]
	v_mfma_f32_16x16x32_bf16 v[6:9], v[178:181], v[194:197], v[6:9]
	v_mfma_f32_16x16x32_bf16 v[66:69], v[170:173], v[202:205], v[66:69]
	v_mfma_f32_16x16x32_bf16 v[2:5], v[178:181], v[202:205], v[2:5]
	v_mfma_f32_16x16x32_bf16 v[82:85], v[170:173], v[230:233], v[82:85]
	v_mfma_f32_16x16x32_bf16 v[14:17], v[178:181], v[230:233], v[14:17]
	v_mfma_f32_16x16x32_bf16 v[90:93], v[174:177], v[190:193], v[90:93]
	v_mfma_f32_16x16x32_bf16 v[26:29], v[182:185], v[190:193], v[26:29]
	v_mfma_f32_16x16x32_bf16 v[70:73], v[174:177], v[198:201], v[70:73]
	v_mfma_f32_16x16x32_bf16 v[6:9], v[182:185], v[198:201], v[6:9]
	v_mfma_f32_16x16x32_bf16 v[66:69], v[174:177], v[226:229], v[66:69]
	v_mfma_f32_16x16x32_bf16 v[2:5], v[182:185], v[226:229], v[2:5]
	v_mfma_f32_16x16x32_bf16 v[82:85], v[174:177], v[234:237], v[82:85]
	v_mfma_f32_16x16x32_bf16 v[14:17], v[182:185], v[234:237], v[14:17]
	s_setprio 0
	s_barrier
	s_add_i32 s46, 0, 0x18000
	v_add_u32_e32 v0, s46, v223
	s_add_i32 s47, 0, 0x1c000
	ds_read_b128 v[130:133], v0
	ds_read_b128 v[134:137], v0 offset:1024
	ds_read_b128 v[150:153], v0 offset:2048
	ds_read_b128 v[154:157], v0 offset:3072
	v_add_u32_e32 v0, s47, v223
	ds_read_b128 v[170:173], v0
	ds_read_b128 v[174:177], v0 offset:1024
	ds_read_b128 v[178:181], v0 offset:2048
	ds_read_b128 v[182:185], v0 offset:3072
	s_add_u32 s4, s4, 0x40000
	s_addc_u32 s5, s5, 0
	s_mov_b32 m0, s15
	v_lshl_add_u64 v[242:243], s[4:5], 0, v[138:139]
	ds_read_b128 v[186:189], v225 offset:32768
	ds_read_b128 v[190:193], v225 offset:33792
	ds_read_b128 v[194:197], v225 offset:34816
	ds_read_b128 v[198:201], v225 offset:35840
	ds_read_b128 v[202:205], v225 offset:36864
	ds_read_b128 v[226:229], v225 offset:37888
	ds_read_b128 v[230:233], v225 offset:38912
	ds_read_b128 v[234:237], v225 offset:39936
	global_load_lds_dwordx4 v[242:243], off
	v_lshl_add_u64 v[242:243], s[4:5], 0, v[142:143]
	s_mov_b32 m0, s16
	s_nop 0
	global_load_lds_dwordx4 v[242:243], off
	s_waitcnt vmcnt(8)
	s_waitcnt lgkmcnt(0)
	s_barrier
	s_setprio 1
	s_waitcnt lgkmcnt(0)
	v_mfma_f32_16x16x32_bf16 v[126:129], v[130:133], v[186:189], v[126:129]
	v_mfma_f32_16x16x32_bf16 v[62:65], v[150:153], v[186:189], v[62:65]
	v_mfma_f32_16x16x32_bf16 v[110:113], v[130:133], v[194:197], v[110:113]
	v_mfma_f32_16x16x32_bf16 v[46:49], v[150:153], v[194:197], v[46:49]
	v_mfma_f32_16x16x32_bf16 v[106:109], v[130:133], v[202:205], v[106:109]
	v_mfma_f32_16x16x32_bf16 v[42:45], v[150:153], v[202:205], v[42:45]
	v_mfma_f32_16x16x32_bf16 v[118:121], v[130:133], v[230:233], v[118:121]
	v_mfma_f32_16x16x32_bf16 v[54:57], v[150:153], v[230:233], v[54:57]
	v_mfma_f32_16x16x32_bf16 v[126:129], v[134:137], v[190:193], v[126:129]
	v_mfma_f32_16x16x32_bf16 v[62:65], v[154:157], v[190:193], v[62:65]
	v_mfma_f32_16x16x32_bf16 v[110:113], v[134:137], v[198:201], v[110:113]
	v_mfma_f32_16x16x32_bf16 v[46:49], v[154:157], v[198:201], v[46:49]
	v_mfma_f32_16x16x32_bf16 v[106:109], v[134:137], v[226:229], v[106:109]
	v_mfma_f32_16x16x32_bf16 v[42:45], v[154:157], v[226:229], v[42:45]
	v_mfma_f32_16x16x32_bf16 v[118:121], v[134:137], v[234:237], v[118:121]
	v_mfma_f32_16x16x32_bf16 v[54:57], v[154:157], v[234:237], v[54:57]
	s_setprio 0
	s_setprio 1
	v_mfma_f32_16x16x32_bf16 v[122:125], v[170:173], v[186:189], v[122:125]
	v_mfma_f32_16x16x32_bf16 v[58:61], v[178:181], v[186:189], v[58:61]
	v_mfma_f32_16x16x32_bf16 v[102:105], v[170:173], v[194:197], v[102:105]
	v_mfma_f32_16x16x32_bf16 v[38:41], v[178:181], v[194:197], v[38:41]
	v_mfma_f32_16x16x32_bf16 v[98:101], v[170:173], v[202:205], v[98:101]
	v_mfma_f32_16x16x32_bf16 v[34:37], v[178:181], v[202:205], v[34:37]
	v_mfma_f32_16x16x32_bf16 v[114:117], v[170:173], v[230:233], v[114:117]
	v_mfma_f32_16x16x32_bf16 v[50:53], v[178:181], v[230:233], v[50:53]
	v_mfma_f32_16x16x32_bf16 v[122:125], v[174:177], v[190:193], v[122:125]
	v_mfma_f32_16x16x32_bf16 v[58:61], v[182:185], v[190:193], v[58:61]
	v_mfma_f32_16x16x32_bf16 v[102:105], v[174:177], v[198:201], v[102:105]
	v_mfma_f32_16x16x32_bf16 v[38:41], v[182:185], v[198:201], v[38:41]
	v_mfma_f32_16x16x32_bf16 v[98:101], v[174:177], v[226:229], v[98:101]
	v_mfma_f32_16x16x32_bf16 v[34:37], v[182:185], v[226:229], v[34:37]
	v_mfma_f32_16x16x32_bf16 v[114:117], v[174:177], v[234:237], v[114:117]
	v_mfma_f32_16x16x32_bf16 v[50:53], v[182:185], v[234:237], v[50:53]
	s_setprio 0
	s_barrier
	s_add_i32 s4, s46, s12
	v_lshl_add_u64 v[158:159], v[158:159], 0, s[80:81]
	s_mov_b32 m0, s4
	ds_read_b128 v[186:189], v225 offset:49152
	ds_read_b128 v[190:193], v225 offset:50176
	ds_read_b128 v[194:197], v225 offset:51200
	ds_read_b128 v[198:201], v225 offset:52224
	ds_read_b128 v[202:205], v225 offset:53248
	ds_read_b128 v[226:229], v225 offset:54272
	ds_read_b128 v[230:233], v225 offset:55296
	ds_read_b128 v[234:237], v225 offset:56320
	global_load_lds_dwordx4 v[158:159], off
	s_add_i32 m0, s4, 0x2000
	s_add_u32 s0, s0, 0x40080
	v_lshl_add_u64 v[158:159], v[206:207], 0, s[80:81]
	s_addc_u32 s1, s1, 0
	s_add_i32 s4, s47, s12
	global_load_lds_dwordx4 v[158:159], off
	v_lshl_add_u64 v[158:159], s[0:1], 0, v[140:141]
	s_mov_b32 m0, s4
	s_nop 0
	global_load_lds_dwordx4 v[158:159], off
	v_lshl_add_u64 v[158:159], s[0:1], 0, v[144:145]
	s_add_i32 m0, s4, 0x2000
	s_nop 0
	global_load_lds_dwordx4 v[158:159], off
	v_lshl_add_u64 v[158:159], v[238:239], 0, s[80:81]
	s_mov_b32 m0, s22
	s_nop 0
	global_load_lds_dwordx4 v[158:159], off
	v_lshl_add_u64 v[158:159], v[240:241], 0, s[80:81]
	s_mov_b32 m0, s23
	s_nop 0
	global_load_lds_dwordx4 v[158:159], off
	s_waitcnt vmcnt(8)
	s_waitcnt lgkmcnt(0)
	s_barrier
	s_setprio 1
	s_waitcnt lgkmcnt(0)
	v_mfma_f32_16x16x32_bf16 v[94:97], v[130:133], v[186:189], v[94:97]
	v_mfma_f32_16x16x32_bf16 v[30:33], v[150:153], v[186:189], v[30:33]
	v_mfma_f32_16x16x32_bf16 v[78:81], v[130:133], v[194:197], v[78:81]
	v_mfma_f32_16x16x32_bf16 v[18:21], v[150:153], v[194:197], v[18:21]
	v_mfma_f32_16x16x32_bf16 v[74:77], v[130:133], v[202:205], v[74:77]
	v_mfma_f32_16x16x32_bf16 v[10:13], v[150:153], v[202:205], v[10:13]
	v_mfma_f32_16x16x32_bf16 v[86:89], v[130:133], v[230:233], v[86:89]
	v_mfma_f32_16x16x32_bf16 v[22:25], v[150:153], v[230:233], v[22:25]
	v_mfma_f32_16x16x32_bf16 v[94:97], v[134:137], v[190:193], v[94:97]
	v_mfma_f32_16x16x32_bf16 v[30:33], v[154:157], v[190:193], v[30:33]
	v_mfma_f32_16x16x32_bf16 v[78:81], v[134:137], v[198:201], v[78:81]
	v_mfma_f32_16x16x32_bf16 v[18:21], v[154:157], v[198:201], v[18:21]
	v_mfma_f32_16x16x32_bf16 v[74:77], v[134:137], v[226:229], v[74:77]
	v_mfma_f32_16x16x32_bf16 v[10:13], v[154:157], v[226:229], v[10:13]
	v_mfma_f32_16x16x32_bf16 v[86:89], v[134:137], v[234:237], v[86:89]
	v_mfma_f32_16x16x32_bf16 v[22:25], v[154:157], v[234:237], v[22:25]
	s_setprio 0
	s_setprio 1
	v_mfma_f32_16x16x32_bf16 v[90:93], v[170:173], v[186:189], v[90:93]
	v_mfma_f32_16x16x32_bf16 v[26:29], v[178:181], v[186:189], v[26:29]
	v_mfma_f32_16x16x32_bf16 v[70:73], v[170:173], v[194:197], v[70:73]
	v_mfma_f32_16x16x32_bf16 v[6:9], v[178:181], v[194:197], v[6:9]
	v_mfma_f32_16x16x32_bf16 v[66:69], v[170:173], v[202:205], v[66:69]
	v_mfma_f32_16x16x32_bf16 v[2:5], v[178:181], v[202:205], v[2:5]
	v_mfma_f32_16x16x32_bf16 v[82:85], v[170:173], v[230:233], v[82:85]
	v_mfma_f32_16x16x32_bf16 v[14:17], v[178:181], v[230:233], v[14:17]
	v_mfma_f32_16x16x32_bf16 v[90:93], v[174:177], v[190:193], v[90:93]
	v_mfma_f32_16x16x32_bf16 v[26:29], v[182:185], v[190:193], v[26:29]
	v_mfma_f32_16x16x32_bf16 v[70:73], v[174:177], v[198:201], v[70:73]
	v_mfma_f32_16x16x32_bf16 v[6:9], v[182:185], v[198:201], v[6:9]
	v_mfma_f32_16x16x32_bf16 v[66:69], v[174:177], v[226:229], v[66:69]
	v_mfma_f32_16x16x32_bf16 v[2:5], v[182:185], v[226:229], v[2:5]
	v_mfma_f32_16x16x32_bf16 v[82:85], v[174:177], v[234:237], v[82:85]
	v_mfma_f32_16x16x32_bf16 v[14:17], v[182:185], v[234:237], v[14:17]
	s_setprio 0
	s_barrier
	s_add_i32 s35, s35, 2
	s_add_u32 s42, s42, 0x100
	s_addc_u32 s43, s43, 0
	s_add_u32 s29, s29, 0x100
	s_addc_u32 s34, s34, 0
	s_cmp_gt_u32 s35, 13
	s_cbranch_scc0 .LBB0_106
	s_and_b64 vcc, exec, s[56:57]
	s_cbranch_vccz .LBB0_109
	s_barrier

.LBB0_662:
	s_add_u32 s0, s56, 0x100
	s_addc_u32 s1, s57, 0
	s_add_i32 s28, 0, 0x10000
	s_cmp_eq_u32 s27, 40
	s_cselect_b32 s5, s45, s1
	s_cselect_b32 s4, s44, s0
	s_cselect_b32 s3, s55, s26
	s_cselect_b32 s2, s54, s25
	s_add_i32 s34, 0, 0x14000
	v_add_u32_e32 v126, s28, v189
	v_add_u32_e32 v178, s34, v189
	ds_read_b128 v[114:117], v126
	ds_read_b128 v[118:121], v126 offset:1024
	ds_read_b128 v[122:125], v126 offset:2048
	ds_read_b128 v[126:129], v126 offset:3072
	ds_read_b128 v[130:133], v178
	ds_read_b128 v[134:137], v178 offset:1024
	ds_read_b128 v[174:177], v178 offset:2048
	ds_read_b128 v[178:181], v178 offset:3072
	v_lshl_add_u64 v[186:187], s[56:57], 0, v[170:171]
	s_add_i32 m0, s14, 0xc000
	ds_read_b128 v[182:185], v191
	ds_read_b128 v[192:195], v191 offset:1024
	ds_read_b128 v[196:199], v191 offset:2048
	ds_read_b128 v[200:203], v191 offset:3072
	ds_read_b128 v[204:207], v191 offset:4096
	ds_read_b128 v[224:227], v191 offset:5120
	ds_read_b128 v[228:231], v191 offset:6144
	ds_read_b128 v[232:235], v191 offset:7168
	global_load_lds_dwordx4 v[186:187], off
	v_lshl_add_u64 v[186:187], s[56:57], 0, v[172:173]
	s_add_i32 m0, s14, 0xe000
	s_nop 0
	global_load_lds_dwordx4 v[186:187], off
	s_cmp_lg_u32 s27, -2
	s_cbranch_scc1 .Lwt__662_0
	s_cmp_lt_u32 s20, 2
	s_cbranch_scc0 .Lws__662_0

.Lws__662_0:
	s_waitcnt lgkmcnt(0)
	s_barrier
	s_setprio 1
	s_waitcnt lgkmcnt(0)
	v_mfma_f32_16x16x32_bf16 v[150:153], v[114:117], v[182:185], v[150:153]
	v_mfma_f32_16x16x32_bf16 v[146:149], v[122:125], v[182:185], v[146:149]
	v_mfma_f32_16x16x32_bf16 v[110:113], v[114:117], v[196:199], v[110:113]
	v_mfma_f32_16x16x32_bf16 v[106:109], v[122:125], v[196:199], v[106:109]
	v_mfma_f32_16x16x32_bf16 v[94:97], v[114:117], v[204:207], v[94:97]
	v_mfma_f32_16x16x32_bf16 v[90:93], v[122:125], v[204:207], v[90:93]
	v_mfma_f32_16x16x32_bf16 v[78:81], v[114:117], v[228:231], v[78:81]
	v_mfma_f32_16x16x32_bf16 v[74:77], v[122:125], v[228:231], v[74:77]
	v_mfma_f32_16x16x32_bf16 v[150:153], v[118:121], v[192:195], v[150:153]
	v_mfma_f32_16x16x32_bf16 v[146:149], v[126:129], v[192:195], v[146:149]
	v_mfma_f32_16x16x32_bf16 v[110:113], v[118:121], v[200:203], v[110:113]
	v_mfma_f32_16x16x32_bf16 v[106:109], v[126:129], v[200:203], v[106:109]
	v_mfma_f32_16x16x32_bf16 v[94:97], v[118:121], v[224:227], v[94:97]
	v_mfma_f32_16x16x32_bf16 v[90:93], v[126:129], v[224:227], v[90:93]
	v_mfma_f32_16x16x32_bf16 v[78:81], v[118:121], v[232:235], v[78:81]
	v_mfma_f32_16x16x32_bf16 v[74:77], v[126:129], v[232:235], v[74:77]
	s_setprio 0
	s_setprio 1
	v_mfma_f32_16x16x32_bf16 v[142:145], v[130:133], v[182:185], v[142:145]
	v_mfma_f32_16x16x32_bf16 v[138:141], v[174:177], v[182:185], v[138:141]
	v_mfma_f32_16x16x32_bf16 v[102:105], v[130:133], v[196:199], v[102:105]
	v_mfma_f32_16x16x32_bf16 v[98:101], v[174:177], v[196:199], v[98:101]
	v_mfma_f32_16x16x32_bf16 v[86:89], v[130:133], v[204:207], v[86:89]
	v_mfma_f32_16x16x32_bf16 v[82:85], v[174:177], v[204:207], v[82:85]
	v_mfma_f32_16x16x32_bf16 v[70:73], v[130:133], v[228:231], v[70:73]
	v_mfma_f32_16x16x32_bf16 v[66:69], v[174:177], v[228:231], v[66:69]
	v_mfma_f32_16x16x32_bf16 v[142:145], v[134:137], v[192:195], v[142:145]
	v_mfma_f32_16x16x32_bf16 v[138:141], v[178:181], v[192:195], v[138:141]
	v_mfma_f32_16x16x32_bf16 v[102:105], v[134:137], v[200:203], v[102:105]
	v_mfma_f32_16x16x32_bf16 v[98:101], v[178:181], v[200:203], v[98:101]
	v_mfma_f32_16x16x32_bf16 v[86:89], v[134:137], v[224:227], v[86:89]
	v_mfma_f32_16x16x32_bf16 v[82:85], v[178:181], v[224:227], v[82:85]
	v_mfma_f32_16x16x32_bf16 v[70:73], v[134:137], v[232:235], v[70:73]
	v_mfma_f32_16x16x32_bf16 v[66:69], v[178:181], v[232:235], v[66:69]
	s_setprio 0
	s_barrier
	s_add_i32 s28, s28, s13
	v_lshl_add_u64 v[186:187], s[2:3], 0, v[0:1]
	s_mov_b32 m0, s28
	ds_read_b128 v[182:185], v191 offset:16384
	ds_read_b128 v[192:195], v191 offset:17408
	ds_read_b128 v[196:199], v191 offset:18432
	ds_read_b128 v[200:203], v191 offset:19456
	ds_read_b128 v[204:207], v191 offset:20480
	ds_read_b128 v[224:227], v191 offset:21504
	ds_read_b128 v[228:231], v191 offset:22528
	ds_read_b128 v[232:235], v191 offset:23552
	global_load_lds_dwordx4 v[186:187], off
	s_add_i32 m0, s28, 0x2000
	s_add_u32 s28, s2, 0xb0000
	v_lshl_add_u64 v[236:237], s[2:3], 0, v[158:159]
	s_addc_u32 s29, s3, 0
	s_add_i32 s34, s34, s13
	global_load_lds_dwordx4 v[236:237], off
	v_lshl_add_u64 v[238:239], s[28:29], 0, v[0:1]
	s_mov_b32 m0, s34
	v_lshl_add_u64 v[240:241], s[4:5], 0, v[156:157]
	global_load_lds_dwordx4 v[238:239], off
	v_lshl_add_u64 v[238:239], s[28:29], 0, v[158:159]
	s_add_i32 m0, s34, 0x2000
	s_nop 0
	global_load_lds_dwordx4 v[238:239], off
	v_lshl_add_u64 v[238:239], s[4:5], 0, v[154:155]
	s_mov_b32 m0, s14
	s_nop 0
	global_load_lds_dwordx4 v[238:239], off
	s_mov_b32 m0, s15
	s_nop 0
	global_load_lds_dwordx4 v[240:241], off
	s_cmp_lg_u32 s27, -2
	s_cbranch_scc1 .Lwt__662_1
	s_cmp_lt_u32 s20, 2
	s_cbranch_scc0 .Lws__662_1

.Lws__662_1:
	s_waitcnt lgkmcnt(0)
	s_barrier
	s_setprio 1
	s_waitcnt lgkmcnt(0)
	v_mfma_f32_16x16x32_bf16 v[62:65], v[114:117], v[182:185], v[62:65]
	v_mfma_f32_16x16x32_bf16 v[58:61], v[122:125], v[182:185], v[58:61]
	v_mfma_f32_16x16x32_bf16 v[46:49], v[114:117], v[196:199], v[46:49]
	v_mfma_f32_16x16x32_bf16 v[42:45], v[122:125], v[196:199], v[42:45]
	v_mfma_f32_16x16x32_bf16 v[30:33], v[114:117], v[204:207], v[30:33]
	v_mfma_f32_16x16x32_bf16 v[26:29], v[122:125], v[204:207], v[26:29]
	v_mfma_f32_16x16x32_bf16 v[14:17], v[114:117], v[228:231], v[14:17]
	v_mfma_f32_16x16x32_bf16 v[10:13], v[122:125], v[228:231], v[10:13]
	v_mfma_f32_16x16x32_bf16 v[62:65], v[118:121], v[192:195], v[62:65]
	v_mfma_f32_16x16x32_bf16 v[58:61], v[126:129], v[192:195], v[58:61]
	v_mfma_f32_16x16x32_bf16 v[46:49], v[118:121], v[200:203], v[46:49]
	v_mfma_f32_16x16x32_bf16 v[42:45], v[126:129], v[200:203], v[42:45]
	v_mfma_f32_16x16x32_bf16 v[30:33], v[118:121], v[224:227], v[30:33]
	v_mfma_f32_16x16x32_bf16 v[26:29], v[126:129], v[224:227], v[26:29]
	v_mfma_f32_16x16x32_bf16 v[14:17], v[118:121], v[232:235], v[14:17]
	v_mfma_f32_16x16x32_bf16 v[10:13], v[126:129], v[232:235], v[10:13]
	s_setprio 0
	s_setprio 1
	v_mfma_f32_16x16x32_bf16 v[54:57], v[130:133], v[182:185], v[54:57]
	v_mfma_f32_16x16x32_bf16 v[50:53], v[174:177], v[182:185], v[50:53]
	v_mfma_f32_16x16x32_bf16 v[38:41], v[130:133], v[196:199], v[38:41]
	v_mfma_f32_16x16x32_bf16 v[34:37], v[174:177], v[196:199], v[34:37]
	v_mfma_f32_16x16x32_bf16 v[22:25], v[130:133], v[204:207], v[22:25]
	v_mfma_f32_16x16x32_bf16 v[18:21], v[174:177], v[204:207], v[18:21]
	v_mfma_f32_16x16x32_bf16 v[6:9], v[130:133], v[228:231], v[6:9]
	v_mfma_f32_16x16x32_bf16 v[2:5], v[174:177], v[228:231], v[2:5]
	v_mfma_f32_16x16x32_bf16 v[54:57], v[134:137], v[192:195], v[54:57]
	v_mfma_f32_16x16x32_bf16 v[50:53], v[178:181], v[192:195], v[50:53]
	v_mfma_f32_16x16x32_bf16 v[38:41], v[134:137], v[200:203], v[38:41]
	v_mfma_f32_16x16x32_bf16 v[34:37], v[178:181], v[200:203], v[34:37]
	v_mfma_f32_16x16x32_bf16 v[22:25], v[134:137], v[224:227], v[22:25]
	v_mfma_f32_16x16x32_bf16 v[18:21], v[178:181], v[224:227], v[18:21]
	v_mfma_f32_16x16x32_bf16 v[6:9], v[134:137], v[232:235], v[6:9]
	v_mfma_f32_16x16x32_bf16 v[2:5], v[178:181], v[232:235], v[2:5]
	s_setprio 0
	s_barrier
	s_add_i32 s28, 0, 0x18000
	s_add_i32 s29, 0, 0x1c000
	v_add_u32_e32 v126, s28, v189
	v_add_u32_e32 v178, s29, v189
	ds_read_b128 v[114:117], v126
	ds_read_b128 v[118:121], v126 offset:1024
	ds_read_b128 v[122:125], v126 offset:2048
	ds_read_b128 v[126:129], v126 offset:3072
	ds_read_b128 v[130:133], v178
	ds_read_b128 v[134:137], v178 offset:1024
	ds_read_b128 v[174:177], v178 offset:2048
	ds_read_b128 v[178:181], v178 offset:3072
	s_add_u32 s4, s4, 0xb0000
	s_addc_u32 s5, s5, 0
	s_mov_b32 m0, s16
	v_lshl_add_u64 v[242:243], s[4:5], 0, v[154:155]
	ds_read_b128 v[182:185], v191 offset:32768
	ds_read_b128 v[192:195], v191 offset:33792
	ds_read_b128 v[196:199], v191 offset:34816
	ds_read_b128 v[200:203], v191 offset:35840
	ds_read_b128 v[204:207], v191 offset:36864
	ds_read_b128 v[224:227], v191 offset:37888
	ds_read_b128 v[228:231], v191 offset:38912
	ds_read_b128 v[232:235], v191 offset:39936
	global_load_lds_dwordx4 v[242:243], off
	v_lshl_add_u64 v[242:243], s[4:5], 0, v[156:157]
	s_mov_b32 m0, s17
	s_nop 0
	global_load_lds_dwordx4 v[242:243], off
	s_waitcnt vmcnt(8)
	s_waitcnt lgkmcnt(0)
	s_barrier
	s_setprio 1
	s_waitcnt lgkmcnt(0)
	v_mfma_f32_16x16x32_bf16 v[150:153], v[114:117], v[182:185], v[150:153]
	v_mfma_f32_16x16x32_bf16 v[146:149], v[122:125], v[182:185], v[146:149]
	v_mfma_f32_16x16x32_bf16 v[110:113], v[114:117], v[196:199], v[110:113]
	v_mfma_f32_16x16x32_bf16 v[106:109], v[122:125], v[196:199], v[106:109]
	v_mfma_f32_16x16x32_bf16 v[94:97], v[114:117], v[204:207], v[94:97]
	v_mfma_f32_16x16x32_bf16 v[90:93], v[122:125], v[204:207], v[90:93]
	v_mfma_f32_16x16x32_bf16 v[78:81], v[114:117], v[228:231], v[78:81]
	v_mfma_f32_16x16x32_bf16 v[74:77], v[122:125], v[228:231], v[74:77]
	v_mfma_f32_16x16x32_bf16 v[150:153], v[118:121], v[192:195], v[150:153]
	v_mfma_f32_16x16x32_bf16 v[146:149], v[126:129], v[192:195], v[146:149]
	v_mfma_f32_16x16x32_bf16 v[110:113], v[118:121], v[200:203], v[110:113]
	v_mfma_f32_16x16x32_bf16 v[106:109], v[126:129], v[200:203], v[106:109]
	v_mfma_f32_16x16x32_bf16 v[94:97], v[118:121], v[224:227], v[94:97]
	v_mfma_f32_16x16x32_bf16 v[90:93], v[126:129], v[224:227], v[90:93]
	v_mfma_f32_16x16x32_bf16 v[78:81], v[118:121], v[232:235], v[78:81]
	v_mfma_f32_16x16x32_bf16 v[74:77], v[126:129], v[232:235], v[74:77]
	s_setprio 0
	s_setprio 1
	v_mfma_f32_16x16x32_bf16 v[142:145], v[130:133], v[182:185], v[142:145]
	v_mfma_f32_16x16x32_bf16 v[138:141], v[174:177], v[182:185], v[138:141]
	v_mfma_f32_16x16x32_bf16 v[102:105], v[130:133], v[196:199], v[102:105]
	v_mfma_f32_16x16x32_bf16 v[98:101], v[174:177], v[196:199], v[98:101]
	v_mfma_f32_16x16x32_bf16 v[86:89], v[130:133], v[204:207], v[86:89]
	v_mfma_f32_16x16x32_bf16 v[82:85], v[174:177], v[204:207], v[82:85]
	v_mfma_f32_16x16x32_bf16 v[70:73], v[130:133], v[228:231], v[70:73]
	v_mfma_f32_16x16x32_bf16 v[66:69], v[174:177], v[228:231], v[66:69]
	v_mfma_f32_16x16x32_bf16 v[142:145], v[134:137], v[192:195], v[142:145]
	v_mfma_f32_16x16x32_bf16 v[138:141], v[178:181], v[192:195], v[138:141]
	v_mfma_f32_16x16x32_bf16 v[102:105], v[134:137], v[200:203], v[102:105]
	v_mfma_f32_16x16x32_bf16 v[98:101], v[178:181], v[200:203], v[98:101]
	v_mfma_f32_16x16x32_bf16 v[86:89], v[134:137], v[224:227], v[86:89]
	v_mfma_f32_16x16x32_bf16 v[82:85], v[178:181], v[224:227], v[82:85]
	v_mfma_f32_16x16x32_bf16 v[70:73], v[134:137], v[232:235], v[70:73]
	v_mfma_f32_16x16x32_bf16 v[66:69], v[178:181], v[232:235], v[66:69]
	s_setprio 0
	s_barrier
	s_add_i32 s4, s28, s13
	v_lshl_add_u64 v[186:187], v[186:187], 0, s[60:61]
	s_mov_b32 m0, s4
	ds_read_b128 v[182:185], v191 offset:49152
	ds_read_b128 v[192:195], v191 offset:50176
	ds_read_b128 v[196:199], v191 offset:51200
	ds_read_b128 v[200:203], v191 offset:52224
	ds_read_b128 v[204:207], v191 offset:53248
	ds_read_b128 v[224:227], v191 offset:54272
	ds_read_b128 v[228:231], v191 offset:55296
	ds_read_b128 v[232:235], v191 offset:56320
	global_load_lds_dwordx4 v[186:187], off
	s_add_i32 m0, s4, 0x2000
	s_add_u32 s2, s2, 0xb0080
	v_lshl_add_u64 v[186:187], v[236:237], 0, s[60:61]
	s_addc_u32 s3, s3, 0
	s_add_i32 s4, s29, s13
	global_load_lds_dwordx4 v[186:187], off
	v_lshl_add_u64 v[186:187], s[2:3], 0, v[0:1]
	s_mov_b32 m0, s4
	s_nop 0
	global_load_lds_dwordx4 v[186:187], off
	v_lshl_add_u64 v[186:187], s[2:3], 0, v[158:159]
	s_add_i32 m0, s4, 0x2000
	s_nop 0
	global_load_lds_dwordx4 v[186:187], off
	v_lshl_add_u64 v[186:187], v[238:239], 0, s[60:61]
	s_mov_b32 m0, s18
	s_nop 0
	global_load_lds_dwordx4 v[186:187], off
	v_lshl_add_u64 v[186:187], v[240:241], 0, s[60:61]
	s_mov_b32 m0, s19
	s_nop 0
	global_load_lds_dwordx4 v[186:187], off
	s_waitcnt vmcnt(8)
	s_waitcnt lgkmcnt(0)
	s_barrier
	s_setprio 1
	s_waitcnt lgkmcnt(0)
	v_mfma_f32_16x16x32_bf16 v[62:65], v[114:117], v[182:185], v[62:65]
	v_mfma_f32_16x16x32_bf16 v[58:61], v[122:125], v[182:185], v[58:61]
	v_mfma_f32_16x16x32_bf16 v[46:49], v[114:117], v[196:199], v[46:49]
	v_mfma_f32_16x16x32_bf16 v[42:45], v[122:125], v[196:199], v[42:45]
	v_mfma_f32_16x16x32_bf16 v[30:33], v[114:117], v[204:207], v[30:33]
	v_mfma_f32_16x16x32_bf16 v[26:29], v[122:125], v[204:207], v[26:29]
	v_mfma_f32_16x16x32_bf16 v[14:17], v[114:117], v[228:231], v[14:17]
	v_mfma_f32_16x16x32_bf16 v[10:13], v[122:125], v[228:231], v[10:13]
	v_mfma_f32_16x16x32_bf16 v[62:65], v[118:121], v[192:195], v[62:65]
	v_mfma_f32_16x16x32_bf16 v[58:61], v[126:129], v[192:195], v[58:61]
	v_mfma_f32_16x16x32_bf16 v[46:49], v[118:121], v[200:203], v[46:49]
	v_mfma_f32_16x16x32_bf16 v[42:45], v[126:129], v[200:203], v[42:45]
	v_mfma_f32_16x16x32_bf16 v[30:33], v[118:121], v[224:227], v[30:33]
	v_mfma_f32_16x16x32_bf16 v[26:29], v[126:129], v[224:227], v[26:29]
	v_mfma_f32_16x16x32_bf16 v[14:17], v[118:121], v[232:235], v[14:17]
	v_mfma_f32_16x16x32_bf16 v[10:13], v[126:129], v[232:235], v[10:13]
	s_setprio 0
	s_setprio 1
	v_mfma_f32_16x16x32_bf16 v[54:57], v[130:133], v[182:185], v[54:57]
	v_mfma_f32_16x16x32_bf16 v[50:53], v[174:177], v[182:185], v[50:53]
	v_mfma_f32_16x16x32_bf16 v[38:41], v[130:133], v[196:199], v[38:41]
	v_mfma_f32_16x16x32_bf16 v[34:37], v[174:177], v[196:199], v[34:37]
	v_mfma_f32_16x16x32_bf16 v[22:25], v[130:133], v[204:207], v[22:25]
	v_mfma_f32_16x16x32_bf16 v[18:21], v[174:177], v[204:207], v[18:21]
	v_mfma_f32_16x16x32_bf16 v[6:9], v[130:133], v[228:231], v[6:9]
	v_mfma_f32_16x16x32_bf16 v[2:5], v[174:177], v[228:231], v[2:5]
	v_mfma_f32_16x16x32_bf16 v[54:57], v[134:137], v[192:195], v[54:57]
	v_mfma_f32_16x16x32_bf16 v[50:53], v[178:181], v[192:195], v[50:53]
	v_mfma_f32_16x16x32_bf16 v[38:41], v[134:137], v[200:203], v[38:41]
	v_mfma_f32_16x16x32_bf16 v[34:37], v[178:181], v[200:203], v[34:37]
	v_mfma_f32_16x16x32_bf16 v[22:25], v[134:137], v[224:227], v[22:25]
	v_mfma_f32_16x16x32_bf16 v[18:21], v[178:181], v[224:227], v[18:21]
	v_mfma_f32_16x16x32_bf16 v[6:9], v[134:137], v[232:235], v[6:9]
	v_mfma_f32_16x16x32_bf16 v[2:5], v[178:181], v[232:235], v[2:5]
	s_setprio 0
	s_barrier
	s_add_i32 s27, s27, 2
	s_add_u32 s25, s25, 0x100
	s_addc_u32 s26, s26, 0
	s_cmp_gt_u32 s27, 41
	s_mov_b64 s[56:57], s[0:1]
	s_cbranch_scc0 .LBB0_662
	s_and_b64 vcc, exec, s[48:49]
	s_cbranch_vccz .LBB0_665
	s_barrier

.LBB0_698:
	s_add_u32 s0, s56, 0xfffc0080
	s_addc_u32 s1, s57, -1
	s_add_i32 s43, 0, 0x10000
	s_cmp_eq_u32 s39, 12
	s_cselect_b32 s7, s24, s1
	s_cselect_b32 s6, s25, s0
	s_cselect_b32 s1, s28, s35
	s_cselect_b32 s0, s29, s34
	s_add_i32 s45, 0, 0x14000
	v_add_u32_e32 v152, s43, v175
	v_add_u32_e32 v182, s45, v175
	ds_read_b128 v[140:143], v152
	ds_read_b128 v[144:147], v152 offset:1024
	ds_read_b128 v[148:151], v152 offset:2048
	ds_read_b128 v[152:155], v152 offset:3072
	ds_read_b128 v[156:159], v182
	ds_read_b128 v[170:173], v182 offset:1024
	ds_read_b128 v[178:181], v182 offset:2048
	ds_read_b128 v[182:185], v182 offset:3072
	v_lshl_add_u64 v[206:207], s[56:57], 0, v[136:137]
	s_add_i32 m0, s13, 0xc000
	ds_read_b128 v[186:189], v177
	ds_read_b128 v[190:193], v177 offset:1024
	ds_read_b128 v[194:197], v177 offset:2048
	ds_read_b128 v[198:201], v177 offset:3072
	ds_read_b128 v[202:205], v177 offset:4096
	ds_read_b128 v[224:227], v177 offset:5120
	ds_read_b128 v[228:231], v177 offset:6144
	ds_read_b128 v[232:235], v177 offset:7168
	global_load_lds_dwordx4 v[206:207], off
	v_lshl_add_u64 v[206:207], s[56:57], 0, v[138:139]
	s_add_i32 m0, s13, 0xe000
	s_nop 0
	global_load_lds_dwordx4 v[206:207], off
	s_cmp_lg_u32 s39, -2
	s_cbranch_scc1 .Lwt__698_0
	s_cmp_lt_u32 s23, 2
	s_cbranch_scc0 .Lws__698_0

.Lws__698_0:
	s_waitcnt lgkmcnt(0)
	s_barrier
	s_setprio 1
	s_waitcnt lgkmcnt(0)
	v_mfma_f32_16x16x32_bf16 v[126:129], v[140:143], v[186:189], v[126:129]
	v_mfma_f32_16x16x32_bf16 v[122:125], v[148:151], v[186:189], v[122:125]
	v_mfma_f32_16x16x32_bf16 v[110:113], v[140:143], v[194:197], v[110:113]
	v_mfma_f32_16x16x32_bf16 v[106:109], v[148:151], v[194:197], v[106:109]
	v_mfma_f32_16x16x32_bf16 v[94:97], v[140:143], v[202:205], v[94:97]
	v_mfma_f32_16x16x32_bf16 v[90:93], v[148:151], v[202:205], v[90:93]
	v_mfma_f32_16x16x32_bf16 v[78:81], v[140:143], v[228:231], v[78:81]
	v_mfma_f32_16x16x32_bf16 v[74:77], v[148:151], v[228:231], v[74:77]
	v_mfma_f32_16x16x32_bf16 v[126:129], v[144:147], v[190:193], v[126:129]
	v_mfma_f32_16x16x32_bf16 v[122:125], v[152:155], v[190:193], v[122:125]
	v_mfma_f32_16x16x32_bf16 v[110:113], v[144:147], v[198:201], v[110:113]
	v_mfma_f32_16x16x32_bf16 v[106:109], v[152:155], v[198:201], v[106:109]
	v_mfma_f32_16x16x32_bf16 v[94:97], v[144:147], v[224:227], v[94:97]
	v_mfma_f32_16x16x32_bf16 v[90:93], v[152:155], v[224:227], v[90:93]
	v_mfma_f32_16x16x32_bf16 v[78:81], v[144:147], v[232:235], v[78:81]
	v_mfma_f32_16x16x32_bf16 v[74:77], v[152:155], v[232:235], v[74:77]
	s_setprio 0
	s_setprio 1
	v_mfma_f32_16x16x32_bf16 v[118:121], v[156:159], v[186:189], v[118:121]
	v_mfma_f32_16x16x32_bf16 v[114:117], v[178:181], v[186:189], v[114:117]
	v_mfma_f32_16x16x32_bf16 v[102:105], v[156:159], v[194:197], v[102:105]
	v_mfma_f32_16x16x32_bf16 v[98:101], v[178:181], v[194:197], v[98:101]
	v_mfma_f32_16x16x32_bf16 v[86:89], v[156:159], v[202:205], v[86:89]
	v_mfma_f32_16x16x32_bf16 v[82:85], v[178:181], v[202:205], v[82:85]
	v_mfma_f32_16x16x32_bf16 v[70:73], v[156:159], v[228:231], v[70:73]
	v_mfma_f32_16x16x32_bf16 v[66:69], v[178:181], v[228:231], v[66:69]
	v_mfma_f32_16x16x32_bf16 v[118:121], v[170:173], v[190:193], v[118:121]
	v_mfma_f32_16x16x32_bf16 v[114:117], v[182:185], v[190:193], v[114:117]
	v_mfma_f32_16x16x32_bf16 v[102:105], v[170:173], v[198:201], v[102:105]
	v_mfma_f32_16x16x32_bf16 v[98:101], v[182:185], v[198:201], v[98:101]
	v_mfma_f32_16x16x32_bf16 v[86:89], v[170:173], v[224:227], v[86:89]
	v_mfma_f32_16x16x32_bf16 v[82:85], v[182:185], v[224:227], v[82:85]
	v_mfma_f32_16x16x32_bf16 v[70:73], v[170:173], v[232:235], v[70:73]
	v_mfma_f32_16x16x32_bf16 v[66:69], v[182:185], v[232:235], v[66:69]
	s_setprio 0
	s_barrier
	s_add_i32 s43, s43, s10
	v_lshl_add_u64 v[206:207], s[0:1], 0, v[0:1]
	s_mov_b32 m0, s43
	ds_read_b128 v[186:189], v177 offset:16384
	ds_read_b128 v[190:193], v177 offset:17408
	ds_read_b128 v[194:197], v177 offset:18432
	ds_read_b128 v[198:201], v177 offset:19456
	ds_read_b128 v[202:205], v177 offset:20480
	ds_read_b128 v[224:227], v177 offset:21504
	ds_read_b128 v[228:231], v177 offset:22528
	ds_read_b128 v[232:235], v177 offset:23552
	global_load_lds_dwordx4 v[206:207], off
	s_add_i32 m0, s43, 0x2000
	s_add_u32 s46, s0, 0x40000
	v_lshl_add_u64 v[236:237], s[0:1], 0, v[134:135]
	s_addc_u32 s47, s1, 0
	s_add_i32 s43, s45, s10
	global_load_lds_dwordx4 v[236:237], off
	v_lshl_add_u64 v[238:239], s[46:47], 0, v[0:1]
	s_mov_b32 m0, s43
	v_lshl_add_u64 v[240:241], s[6:7], 0, v[132:133]
	global_load_lds_dwordx4 v[238:239], off
	v_lshl_add_u64 v[238:239], s[46:47], 0, v[134:135]
	s_add_i32 m0, s43, 0x2000
	s_nop 0
	global_load_lds_dwordx4 v[238:239], off
	v_lshl_add_u64 v[238:239], s[6:7], 0, v[130:131]
	s_mov_b32 m0, s13
	s_nop 0
	global_load_lds_dwordx4 v[238:239], off
	s_mov_b32 m0, s14
	s_nop 0
	global_load_lds_dwordx4 v[240:241], off
	s_cmp_lg_u32 s39, -2
	s_cbranch_scc1 .Lwt__698_1
	s_cmp_lt_u32 s23, 2
	s_cbranch_scc0 .Lws__698_1

.Lws__698_1:
	s_waitcnt lgkmcnt(0)
	s_barrier
	s_setprio 1
	s_waitcnt lgkmcnt(0)
	v_mfma_f32_16x16x32_bf16 v[62:65], v[140:143], v[186:189], v[62:65]
	v_mfma_f32_16x16x32_bf16 v[58:61], v[148:151], v[186:189], v[58:61]
	v_mfma_f32_16x16x32_bf16 v[46:49], v[140:143], v[194:197], v[46:49]
	v_mfma_f32_16x16x32_bf16 v[42:45], v[148:151], v[194:197], v[42:45]
	v_mfma_f32_16x16x32_bf16 v[30:33], v[140:143], v[202:205], v[30:33]
	v_mfma_f32_16x16x32_bf16 v[26:29], v[148:151], v[202:205], v[26:29]
	v_mfma_f32_16x16x32_bf16 v[14:17], v[140:143], v[228:231], v[14:17]
	v_mfma_f32_16x16x32_bf16 v[10:13], v[148:151], v[228:231], v[10:13]
	v_mfma_f32_16x16x32_bf16 v[62:65], v[144:147], v[190:193], v[62:65]
	v_mfma_f32_16x16x32_bf16 v[58:61], v[152:155], v[190:193], v[58:61]
	v_mfma_f32_16x16x32_bf16 v[46:49], v[144:147], v[198:201], v[46:49]
	v_mfma_f32_16x16x32_bf16 v[42:45], v[152:155], v[198:201], v[42:45]
	v_mfma_f32_16x16x32_bf16 v[30:33], v[144:147], v[224:227], v[30:33]
	v_mfma_f32_16x16x32_bf16 v[26:29], v[152:155], v[224:227], v[26:29]
	v_mfma_f32_16x16x32_bf16 v[14:17], v[144:147], v[232:235], v[14:17]
	v_mfma_f32_16x16x32_bf16 v[10:13], v[152:155], v[232:235], v[10:13]
	s_setprio 0
	s_setprio 1
	v_mfma_f32_16x16x32_bf16 v[54:57], v[156:159], v[186:189], v[54:57]
	v_mfma_f32_16x16x32_bf16 v[50:53], v[178:181], v[186:189], v[50:53]
	v_mfma_f32_16x16x32_bf16 v[38:41], v[156:159], v[194:197], v[38:41]
	v_mfma_f32_16x16x32_bf16 v[34:37], v[178:181], v[194:197], v[34:37]
	v_mfma_f32_16x16x32_bf16 v[22:25], v[156:159], v[202:205], v[22:25]
	v_mfma_f32_16x16x32_bf16 v[18:21], v[178:181], v[202:205], v[18:21]
	v_mfma_f32_16x16x32_bf16 v[6:9], v[156:159], v[228:231], v[6:9]
	v_mfma_f32_16x16x32_bf16 v[2:5], v[178:181], v[228:231], v[2:5]
	v_mfma_f32_16x16x32_bf16 v[54:57], v[170:173], v[190:193], v[54:57]
	v_mfma_f32_16x16x32_bf16 v[50:53], v[182:185], v[190:193], v[50:53]
	v_mfma_f32_16x16x32_bf16 v[38:41], v[170:173], v[198:201], v[38:41]
	v_mfma_f32_16x16x32_bf16 v[34:37], v[182:185], v[198:201], v[34:37]
	v_mfma_f32_16x16x32_bf16 v[22:25], v[170:173], v[224:227], v[22:25]
	v_mfma_f32_16x16x32_bf16 v[18:21], v[182:185], v[224:227], v[18:21]
	v_mfma_f32_16x16x32_bf16 v[6:9], v[170:173], v[232:235], v[6:9]
	v_mfma_f32_16x16x32_bf16 v[2:5], v[182:185], v[232:235], v[2:5]
	s_setprio 0
	s_barrier
	s_add_i32 s43, 0, 0x18000
	s_add_i32 s45, 0, 0x1c000
	v_add_u32_e32 v152, s43, v175
	v_add_u32_e32 v182, s45, v175
	ds_read_b128 v[140:143], v152
	ds_read_b128 v[144:147], v152 offset:1024
	ds_read_b128 v[148:151], v152 offset:2048
	ds_read_b128 v[152:155], v152 offset:3072
	ds_read_b128 v[156:159], v182
	ds_read_b128 v[170:173], v182 offset:1024
	ds_read_b128 v[178:181], v182 offset:2048
	ds_read_b128 v[182:185], v182 offset:3072
	s_add_u32 s6, s6, 0x40000
	s_addc_u32 s7, s7, 0
	s_mov_b32 m0, s15
	v_lshl_add_u64 v[242:243], s[6:7], 0, v[130:131]
	ds_read_b128 v[186:189], v177 offset:32768
	ds_read_b128 v[190:193], v177 offset:33792
	ds_read_b128 v[194:197], v177 offset:34816
	ds_read_b128 v[198:201], v177 offset:35840
	ds_read_b128 v[202:205], v177 offset:36864
	ds_read_b128 v[224:227], v177 offset:37888
	ds_read_b128 v[228:231], v177 offset:38912
	ds_read_b128 v[232:235], v177 offset:39936
	global_load_lds_dwordx4 v[242:243], off
	v_lshl_add_u64 v[242:243], s[6:7], 0, v[132:133]
	s_mov_b32 m0, s16
	s_nop 0
	global_load_lds_dwordx4 v[242:243], off
	s_waitcnt vmcnt(8)
	s_waitcnt lgkmcnt(0)
	s_barrier
	s_setprio 1
	s_waitcnt lgkmcnt(0)
	v_mfma_f32_16x16x32_bf16 v[126:129], v[140:143], v[186:189], v[126:129]
	v_mfma_f32_16x16x32_bf16 v[122:125], v[148:151], v[186:189], v[122:125]
	v_mfma_f32_16x16x32_bf16 v[110:113], v[140:143], v[194:197], v[110:113]
	v_mfma_f32_16x16x32_bf16 v[106:109], v[148:151], v[194:197], v[106:109]
	v_mfma_f32_16x16x32_bf16 v[94:97], v[140:143], v[202:205], v[94:97]
	v_mfma_f32_16x16x32_bf16 v[90:93], v[148:151], v[202:205], v[90:93]
	v_mfma_f32_16x16x32_bf16 v[78:81], v[140:143], v[228:231], v[78:81]
	v_mfma_f32_16x16x32_bf16 v[74:77], v[148:151], v[228:231], v[74:77]
	v_mfma_f32_16x16x32_bf16 v[126:129], v[144:147], v[190:193], v[126:129]
	v_mfma_f32_16x16x32_bf16 v[122:125], v[152:155], v[190:193], v[122:125]
	v_mfma_f32_16x16x32_bf16 v[110:113], v[144:147], v[198:201], v[110:113]
	v_mfma_f32_16x16x32_bf16 v[106:109], v[152:155], v[198:201], v[106:109]
	v_mfma_f32_16x16x32_bf16 v[94:97], v[144:147], v[224:227], v[94:97]
	v_mfma_f32_16x16x32_bf16 v[90:93], v[152:155], v[224:227], v[90:93]
	v_mfma_f32_16x16x32_bf16 v[78:81], v[144:147], v[232:235], v[78:81]
	v_mfma_f32_16x16x32_bf16 v[74:77], v[152:155], v[232:235], v[74:77]
	s_setprio 0
	s_setprio 1
	v_mfma_f32_16x16x32_bf16 v[118:121], v[156:159], v[186:189], v[118:121]
	v_mfma_f32_16x16x32_bf16 v[114:117], v[178:181], v[186:189], v[114:117]
	v_mfma_f32_16x16x32_bf16 v[102:105], v[156:159], v[194:197], v[102:105]
	v_mfma_f32_16x16x32_bf16 v[98:101], v[178:181], v[194:197], v[98:101]
	v_mfma_f32_16x16x32_bf16 v[86:89], v[156:159], v[202:205], v[86:89]
	v_mfma_f32_16x16x32_bf16 v[82:85], v[178:181], v[202:205], v[82:85]
	v_mfma_f32_16x16x32_bf16 v[70:73], v[156:159], v[228:231], v[70:73]
	v_mfma_f32_16x16x32_bf16 v[66:69], v[178:181], v[228:231], v[66:69]
	v_mfma_f32_16x16x32_bf16 v[118:121], v[170:173], v[190:193], v[118:121]
	v_mfma_f32_16x16x32_bf16 v[114:117], v[182:185], v[190:193], v[114:117]
	v_mfma_f32_16x16x32_bf16 v[102:105], v[170:173], v[198:201], v[102:105]
	v_mfma_f32_16x16x32_bf16 v[98:101], v[182:185], v[198:201], v[98:101]
	v_mfma_f32_16x16x32_bf16 v[86:89], v[170:173], v[224:227], v[86:89]
	v_mfma_f32_16x16x32_bf16 v[82:85], v[182:185], v[224:227], v[82:85]
	v_mfma_f32_16x16x32_bf16 v[70:73], v[170:173], v[232:235], v[70:73]
	v_mfma_f32_16x16x32_bf16 v[66:69], v[182:185], v[232:235], v[66:69]
	s_setprio 0
	s_barrier
	s_add_i32 s6, s43, s10
	v_lshl_add_u64 v[206:207], v[206:207], 0, s[60:61]
	s_mov_b32 m0, s6
	ds_read_b128 v[186:189], v177 offset:49152
	ds_read_b128 v[190:193], v177 offset:50176
	ds_read_b128 v[194:197], v177 offset:51200
	ds_read_b128 v[198:201], v177 offset:52224
	ds_read_b128 v[202:205], v177 offset:53248
	ds_read_b128 v[224:227], v177 offset:54272
	ds_read_b128 v[228:231], v177 offset:55296
	ds_read_b128 v[232:235], v177 offset:56320
	global_load_lds_dwordx4 v[206:207], off
	s_add_i32 m0, s6, 0x2000
	s_add_u32 s0, s0, 0x40080
	v_lshl_add_u64 v[206:207], v[236:237], 0, s[60:61]
	s_addc_u32 s1, s1, 0
	s_add_i32 s6, s45, s10
	global_load_lds_dwordx4 v[206:207], off
	v_lshl_add_u64 v[206:207], s[0:1], 0, v[0:1]
	s_mov_b32 m0, s6
	s_nop 0
	global_load_lds_dwordx4 v[206:207], off
	v_lshl_add_u64 v[206:207], s[0:1], 0, v[134:135]
	s_add_i32 m0, s6, 0x2000
	s_nop 0
	global_load_lds_dwordx4 v[206:207], off
	v_lshl_add_u64 v[206:207], v[238:239], 0, s[60:61]
	s_mov_b32 m0, s19
	s_nop 0
	global_load_lds_dwordx4 v[206:207], off
	v_lshl_add_u64 v[206:207], v[240:241], 0, s[60:61]
	s_mov_b32 m0, s20
	s_nop 0
	global_load_lds_dwordx4 v[206:207], off
	s_waitcnt vmcnt(8)
	s_waitcnt lgkmcnt(0)
	s_barrier
	s_setprio 1
	s_waitcnt lgkmcnt(0)
	v_mfma_f32_16x16x32_bf16 v[62:65], v[140:143], v[186:189], v[62:65]
	v_mfma_f32_16x16x32_bf16 v[58:61], v[148:151], v[186:189], v[58:61]
	v_mfma_f32_16x16x32_bf16 v[46:49], v[140:143], v[194:197], v[46:49]
	v_mfma_f32_16x16x32_bf16 v[42:45], v[148:151], v[194:197], v[42:45]
	v_mfma_f32_16x16x32_bf16 v[30:33], v[140:143], v[202:205], v[30:33]
	v_mfma_f32_16x16x32_bf16 v[26:29], v[148:151], v[202:205], v[26:29]
	v_mfma_f32_16x16x32_bf16 v[14:17], v[140:143], v[228:231], v[14:17]
	v_mfma_f32_16x16x32_bf16 v[10:13], v[148:151], v[228:231], v[10:13]
	v_mfma_f32_16x16x32_bf16 v[62:65], v[144:147], v[190:193], v[62:65]
	v_mfma_f32_16x16x32_bf16 v[58:61], v[152:155], v[190:193], v[58:61]
	v_mfma_f32_16x16x32_bf16 v[46:49], v[144:147], v[198:201], v[46:49]
	v_mfma_f32_16x16x32_bf16 v[42:45], v[152:155], v[198:201], v[42:45]
	v_mfma_f32_16x16x32_bf16 v[30:33], v[144:147], v[224:227], v[30:33]
	v_mfma_f32_16x16x32_bf16 v[26:29], v[152:155], v[224:227], v[26:29]
	v_mfma_f32_16x16x32_bf16 v[14:17], v[144:147], v[232:235], v[14:17]
	v_mfma_f32_16x16x32_bf16 v[10:13], v[152:155], v[232:235], v[10:13]
	s_setprio 0
	s_setprio 1
	v_mfma_f32_16x16x32_bf16 v[54:57], v[156:159], v[186:189], v[54:57]
	v_mfma_f32_16x16x32_bf16 v[50:53], v[178:181], v[186:189], v[50:53]
	v_mfma_f32_16x16x32_bf16 v[38:41], v[156:159], v[194:197], v[38:41]
	v_mfma_f32_16x16x32_bf16 v[34:37], v[178:181], v[194:197], v[34:37]
	v_mfma_f32_16x16x32_bf16 v[22:25], v[156:159], v[202:205], v[22:25]
	v_mfma_f32_16x16x32_bf16 v[18:21], v[178:181], v[202:205], v[18:21]
	v_mfma_f32_16x16x32_bf16 v[6:9], v[156:159], v[228:231], v[6:9]
	v_mfma_f32_16x16x32_bf16 v[2:5], v[178:181], v[228:231], v[2:5]
	v_mfma_f32_16x16x32_bf16 v[54:57], v[170:173], v[190:193], v[54:57]
	v_mfma_f32_16x16x32_bf16 v[50:53], v[182:185], v[190:193], v[50:53]
	v_mfma_f32_16x16x32_bf16 v[38:41], v[170:173], v[198:201], v[38:41]
	v_mfma_f32_16x16x32_bf16 v[34:37], v[182:185], v[198:201], v[34:37]
	v_mfma_f32_16x16x32_bf16 v[22:25], v[170:173], v[224:227], v[22:25]
	v_mfma_f32_16x16x32_bf16 v[18:21], v[182:185], v[224:227], v[18:21]
	v_mfma_f32_16x16x32_bf16 v[6:9], v[170:173], v[232:235], v[6:9]
	v_mfma_f32_16x16x32_bf16 v[2:5], v[182:185], v[232:235], v[2:5]
	s_setprio 0
	s_barrier
	s_add_i32 s39, s39, 2
	s_add_u32 s56, s56, 0x100
	s_addc_u32 s57, s57, 0
	s_add_u32 s34, s34, 0x100
	s_addc_u32 s35, s35, 0
	s_cmp_gt_u32 s39, 13
	s_cbranch_scc0 .LBB0_698
	s_and_b64 vcc, exec, s[36:37]
	s_cbranch_vccz .LBB0_701
	s_barrier

.LBB0_778:
	s_add_u32 s0, s42, 0xfffc0080
	s_addc_u32 s1, s43, -1
	s_add_i32 s39, 0, 0x10000
	s_cmp_eq_u32 s35, 12
	s_cselect_b32 s7, s23, s1
	s_cselect_b32 s6, s24, s0
	s_cselect_b32 s1, s25, s34
	s_cselect_b32 s0, s28, s29
	s_add_i32 s45, 0, 0x14000
	v_add_u32_e32 v142, s39, v179
	v_add_u32_e32 v182, s45, v179
	ds_read_b128 v[130:133], v142
	ds_read_b128 v[134:137], v142 offset:1024
	ds_read_b128 v[138:141], v142 offset:2048
	ds_read_b128 v[142:145], v142 offset:3072
	ds_read_b128 v[156:159], v182
	ds_read_b128 v[170:173], v182 offset:1024
	ds_read_b128 v[174:177], v182 offset:2048
	ds_read_b128 v[182:185], v182 offset:3072
	v_lshl_add_u64 v[206:207], s[42:43], 0, v[152:153]
	s_add_i32 m0, s14, 0xc000
	ds_read_b128 v[186:189], v181
	ds_read_b128 v[190:193], v181 offset:1024
	ds_read_b128 v[194:197], v181 offset:2048
	ds_read_b128 v[198:201], v181 offset:3072
	ds_read_b128 v[202:205], v181 offset:4096
	ds_read_b128 v[224:227], v181 offset:5120
	ds_read_b128 v[228:231], v181 offset:6144
	ds_read_b128 v[232:235], v181 offset:7168
	global_load_lds_dwordx4 v[206:207], off
	v_lshl_add_u64 v[206:207], s[42:43], 0, v[154:155]
	s_add_i32 m0, s14, 0xe000
	s_nop 0
	global_load_lds_dwordx4 v[206:207], off
	s_cmp_lg_u32 s35, -2
	s_cbranch_scc1 .Lwt__778_0
	s_cmp_lt_u32 s21, 2
	s_cbranch_scc0 .Lws__778_0

.Lws__778_0:
	s_waitcnt lgkmcnt(0)
	s_barrier
	s_setprio 1
	s_waitcnt lgkmcnt(0)
	v_mfma_f32_16x16x32_bf16 v[126:129], v[130:133], v[186:189], v[126:129]
	v_mfma_f32_16x16x32_bf16 v[122:125], v[138:141], v[186:189], v[122:125]
	v_mfma_f32_16x16x32_bf16 v[114:117], v[130:133], v[194:197], v[114:117]
	v_mfma_f32_16x16x32_bf16 v[106:109], v[138:141], v[194:197], v[106:109]
	v_mfma_f32_16x16x32_bf16 v[98:101], v[130:133], v[202:205], v[98:101]
	v_mfma_f32_16x16x32_bf16 v[90:93], v[138:141], v[202:205], v[90:93]
	v_mfma_f32_16x16x32_bf16 v[82:85], v[130:133], v[228:231], v[82:85]
	v_mfma_f32_16x16x32_bf16 v[74:77], v[138:141], v[228:231], v[74:77]
	v_mfma_f32_16x16x32_bf16 v[126:129], v[134:137], v[190:193], v[126:129]
	v_mfma_f32_16x16x32_bf16 v[122:125], v[142:145], v[190:193], v[122:125]
	v_mfma_f32_16x16x32_bf16 v[114:117], v[134:137], v[198:201], v[114:117]
	v_mfma_f32_16x16x32_bf16 v[106:109], v[142:145], v[198:201], v[106:109]
	v_mfma_f32_16x16x32_bf16 v[98:101], v[134:137], v[224:227], v[98:101]
	v_mfma_f32_16x16x32_bf16 v[90:93], v[142:145], v[224:227], v[90:93]
	v_mfma_f32_16x16x32_bf16 v[82:85], v[134:137], v[232:235], v[82:85]
	v_mfma_f32_16x16x32_bf16 v[74:77], v[142:145], v[232:235], v[74:77]
	s_setprio 0
	s_setprio 1
	v_mfma_f32_16x16x32_bf16 v[118:121], v[156:159], v[186:189], v[118:121]
	v_mfma_f32_16x16x32_bf16 v[110:113], v[174:177], v[186:189], v[110:113]
	v_mfma_f32_16x16x32_bf16 v[102:105], v[156:159], v[194:197], v[102:105]
	v_mfma_f32_16x16x32_bf16 v[94:97], v[174:177], v[194:197], v[94:97]
	v_mfma_f32_16x16x32_bf16 v[86:89], v[156:159], v[202:205], v[86:89]
	v_mfma_f32_16x16x32_bf16 v[78:81], v[174:177], v[202:205], v[78:81]
	v_mfma_f32_16x16x32_bf16 v[70:73], v[156:159], v[228:231], v[70:73]
	v_mfma_f32_16x16x32_bf16 v[66:69], v[174:177], v[228:231], v[66:69]
	v_mfma_f32_16x16x32_bf16 v[118:121], v[170:173], v[190:193], v[118:121]
	v_mfma_f32_16x16x32_bf16 v[110:113], v[182:185], v[190:193], v[110:113]
	v_mfma_f32_16x16x32_bf16 v[102:105], v[170:173], v[198:201], v[102:105]
	v_mfma_f32_16x16x32_bf16 v[94:97], v[182:185], v[198:201], v[94:97]
	v_mfma_f32_16x16x32_bf16 v[86:89], v[170:173], v[224:227], v[86:89]
	v_mfma_f32_16x16x32_bf16 v[78:81], v[182:185], v[224:227], v[78:81]
	v_mfma_f32_16x16x32_bf16 v[70:73], v[170:173], v[232:235], v[70:73]
	v_mfma_f32_16x16x32_bf16 v[66:69], v[182:185], v[232:235], v[66:69]
	s_setprio 0
	s_barrier
	s_add_i32 s39, s39, s12
	v_lshl_add_u64 v[206:207], s[0:1], 0, v[0:1]
	s_mov_b32 m0, s39
	ds_read_b128 v[186:189], v181 offset:16384
	ds_read_b128 v[190:193], v181 offset:17408
	ds_read_b128 v[194:197], v181 offset:18432
	ds_read_b128 v[198:201], v181 offset:19456
	ds_read_b128 v[202:205], v181 offset:20480
	ds_read_b128 v[224:227], v181 offset:21504
	ds_read_b128 v[228:231], v181 offset:22528
	ds_read_b128 v[232:235], v181 offset:23552
	global_load_lds_dwordx4 v[206:207], off
	s_add_i32 m0, s39, 0x2000
	s_add_u32 s46, s0, 0x40000
	v_lshl_add_u64 v[236:237], s[0:1], 0, v[146:147]
	s_addc_u32 s47, s1, 0
	s_add_i32 s39, s45, s12
	global_load_lds_dwordx4 v[236:237], off
	v_lshl_add_u64 v[238:239], s[46:47], 0, v[0:1]
	s_mov_b32 m0, s39
	v_lshl_add_u64 v[240:241], s[6:7], 0, v[148:149]
	global_load_lds_dwordx4 v[238:239], off
	v_lshl_add_u64 v[238:239], s[46:47], 0, v[146:147]
	s_add_i32 m0, s39, 0x2000
	s_nop 0
	global_load_lds_dwordx4 v[238:239], off
	v_lshl_add_u64 v[238:239], s[6:7], 0, v[150:151]
	s_mov_b32 m0, s14
	s_nop 0
	global_load_lds_dwordx4 v[238:239], off
	s_mov_b32 m0, s15
	s_nop 0
	global_load_lds_dwordx4 v[240:241], off
	s_cmp_lg_u32 s35, -2
	s_cbranch_scc1 .Lwt__778_1
	s_cmp_lt_u32 s21, 2
	s_cbranch_scc0 .Lws__778_1

.Lws__778_1:
	s_waitcnt lgkmcnt(0)
	s_barrier
	s_setprio 1
	s_waitcnt lgkmcnt(0)
	v_mfma_f32_16x16x32_bf16 v[62:65], v[130:133], v[186:189], v[62:65]
	v_mfma_f32_16x16x32_bf16 v[58:61], v[138:141], v[186:189], v[58:61]
	v_mfma_f32_16x16x32_bf16 v[50:53], v[130:133], v[194:197], v[50:53]
	v_mfma_f32_16x16x32_bf16 v[42:45], v[138:141], v[194:197], v[42:45]
	v_mfma_f32_16x16x32_bf16 v[34:37], v[130:133], v[202:205], v[34:37]
	v_mfma_f32_16x16x32_bf16 v[26:29], v[138:141], v[202:205], v[26:29]
	v_mfma_f32_16x16x32_bf16 v[18:21], v[130:133], v[228:231], v[18:21]
	v_mfma_f32_16x16x32_bf16 v[10:13], v[138:141], v[228:231], v[10:13]
	v_mfma_f32_16x16x32_bf16 v[62:65], v[134:137], v[190:193], v[62:65]
	v_mfma_f32_16x16x32_bf16 v[58:61], v[142:145], v[190:193], v[58:61]
	v_mfma_f32_16x16x32_bf16 v[50:53], v[134:137], v[198:201], v[50:53]
	v_mfma_f32_16x16x32_bf16 v[42:45], v[142:145], v[198:201], v[42:45]
	v_mfma_f32_16x16x32_bf16 v[34:37], v[134:137], v[224:227], v[34:37]
	v_mfma_f32_16x16x32_bf16 v[26:29], v[142:145], v[224:227], v[26:29]
	v_mfma_f32_16x16x32_bf16 v[18:21], v[134:137], v[232:235], v[18:21]
	v_mfma_f32_16x16x32_bf16 v[10:13], v[142:145], v[232:235], v[10:13]
	s_setprio 0
	s_setprio 1
	v_mfma_f32_16x16x32_bf16 v[54:57], v[156:159], v[186:189], v[54:57]
	v_mfma_f32_16x16x32_bf16 v[46:49], v[174:177], v[186:189], v[46:49]
	v_mfma_f32_16x16x32_bf16 v[38:41], v[156:159], v[194:197], v[38:41]
	v_mfma_f32_16x16x32_bf16 v[30:33], v[174:177], v[194:197], v[30:33]
	v_mfma_f32_16x16x32_bf16 v[22:25], v[156:159], v[202:205], v[22:25]
	v_mfma_f32_16x16x32_bf16 v[14:17], v[174:177], v[202:205], v[14:17]
	v_mfma_f32_16x16x32_bf16 v[6:9], v[156:159], v[228:231], v[6:9]
	v_mfma_f32_16x16x32_bf16 v[2:5], v[174:177], v[228:231], v[2:5]
	v_mfma_f32_16x16x32_bf16 v[54:57], v[170:173], v[190:193], v[54:57]
	v_mfma_f32_16x16x32_bf16 v[46:49], v[182:185], v[190:193], v[46:49]
	v_mfma_f32_16x16x32_bf16 v[38:41], v[170:173], v[198:201], v[38:41]
	v_mfma_f32_16x16x32_bf16 v[30:33], v[182:185], v[198:201], v[30:33]
	v_mfma_f32_16x16x32_bf16 v[22:25], v[170:173], v[224:227], v[22:25]
	v_mfma_f32_16x16x32_bf16 v[14:17], v[182:185], v[224:227], v[14:17]
	v_mfma_f32_16x16x32_bf16 v[6:9], v[170:173], v[232:235], v[6:9]
	v_mfma_f32_16x16x32_bf16 v[2:5], v[182:185], v[232:235], v[2:5]
	s_setprio 0
	s_barrier
	s_add_i32 s39, 0, 0x18000
	s_add_i32 s45, 0, 0x1c000
	v_add_u32_e32 v142, s39, v179
	v_add_u32_e32 v182, s45, v179
	ds_read_b128 v[130:133], v142
	ds_read_b128 v[134:137], v142 offset:1024
	ds_read_b128 v[138:141], v142 offset:2048
	ds_read_b128 v[142:145], v142 offset:3072
	ds_read_b128 v[156:159], v182
	ds_read_b128 v[170:173], v182 offset:1024
	ds_read_b128 v[174:177], v182 offset:2048
	ds_read_b128 v[182:185], v182 offset:3072
	s_add_u32 s6, s6, 0x40000
	s_addc_u32 s7, s7, 0
	s_mov_b32 m0, s16
	v_lshl_add_u64 v[242:243], s[6:7], 0, v[150:151]
	ds_read_b128 v[186:189], v181 offset:32768
	ds_read_b128 v[190:193], v181 offset:33792
	ds_read_b128 v[194:197], v181 offset:34816
	ds_read_b128 v[198:201], v181 offset:35840
	ds_read_b128 v[202:205], v181 offset:36864
	ds_read_b128 v[224:227], v181 offset:37888
	ds_read_b128 v[228:231], v181 offset:38912
	ds_read_b128 v[232:235], v181 offset:39936
	global_load_lds_dwordx4 v[242:243], off
	v_lshl_add_u64 v[242:243], s[6:7], 0, v[148:149]
	s_mov_b32 m0, s17
	s_nop 0
	global_load_lds_dwordx4 v[242:243], off
	s_waitcnt vmcnt(8)
	s_waitcnt lgkmcnt(0)
	s_barrier
	s_setprio 1
	s_waitcnt lgkmcnt(0)
	v_mfma_f32_16x16x32_bf16 v[126:129], v[130:133], v[186:189], v[126:129]
	v_mfma_f32_16x16x32_bf16 v[122:125], v[138:141], v[186:189], v[122:125]
	v_mfma_f32_16x16x32_bf16 v[114:117], v[130:133], v[194:197], v[114:117]
	v_mfma_f32_16x16x32_bf16 v[106:109], v[138:141], v[194:197], v[106:109]
	v_mfma_f32_16x16x32_bf16 v[98:101], v[130:133], v[202:205], v[98:101]
	v_mfma_f32_16x16x32_bf16 v[90:93], v[138:141], v[202:205], v[90:93]
	v_mfma_f32_16x16x32_bf16 v[82:85], v[130:133], v[228:231], v[82:85]
	v_mfma_f32_16x16x32_bf16 v[74:77], v[138:141], v[228:231], v[74:77]
	v_mfma_f32_16x16x32_bf16 v[126:129], v[134:137], v[190:193], v[126:129]
	v_mfma_f32_16x16x32_bf16 v[122:125], v[142:145], v[190:193], v[122:125]
	v_mfma_f32_16x16x32_bf16 v[114:117], v[134:137], v[198:201], v[114:117]
	v_mfma_f32_16x16x32_bf16 v[106:109], v[142:145], v[198:201], v[106:109]
	v_mfma_f32_16x16x32_bf16 v[98:101], v[134:137], v[224:227], v[98:101]
	v_mfma_f32_16x16x32_bf16 v[90:93], v[142:145], v[224:227], v[90:93]
	v_mfma_f32_16x16x32_bf16 v[82:85], v[134:137], v[232:235], v[82:85]
	v_mfma_f32_16x16x32_bf16 v[74:77], v[142:145], v[232:235], v[74:77]
	s_setprio 0
	s_setprio 1
	v_mfma_f32_16x16x32_bf16 v[118:121], v[156:159], v[186:189], v[118:121]
	v_mfma_f32_16x16x32_bf16 v[110:113], v[174:177], v[186:189], v[110:113]
	v_mfma_f32_16x16x32_bf16 v[102:105], v[156:159], v[194:197], v[102:105]
	v_mfma_f32_16x16x32_bf16 v[94:97], v[174:177], v[194:197], v[94:97]
	v_mfma_f32_16x16x32_bf16 v[86:89], v[156:159], v[202:205], v[86:89]
	v_mfma_f32_16x16x32_bf16 v[78:81], v[174:177], v[202:205], v[78:81]
	v_mfma_f32_16x16x32_bf16 v[70:73], v[156:159], v[228:231], v[70:73]
	v_mfma_f32_16x16x32_bf16 v[66:69], v[174:177], v[228:231], v[66:69]
	v_mfma_f32_16x16x32_bf16 v[118:121], v[170:173], v[190:193], v[118:121]
	v_mfma_f32_16x16x32_bf16 v[110:113], v[182:185], v[190:193], v[110:113]
	v_mfma_f32_16x16x32_bf16 v[102:105], v[170:173], v[198:201], v[102:105]
	v_mfma_f32_16x16x32_bf16 v[94:97], v[182:185], v[198:201], v[94:97]
	v_mfma_f32_16x16x32_bf16 v[86:89], v[170:173], v[224:227], v[86:89]
	v_mfma_f32_16x16x32_bf16 v[78:81], v[182:185], v[224:227], v[78:81]
	v_mfma_f32_16x16x32_bf16 v[70:73], v[170:173], v[232:235], v[70:73]
	v_mfma_f32_16x16x32_bf16 v[66:69], v[182:185], v[232:235], v[66:69]
	s_setprio 0
	s_barrier
	s_add_i32 s6, s39, s12
	v_lshl_add_u64 v[206:207], v[206:207], 0, s[56:57]
	s_mov_b32 m0, s6
	ds_read_b128 v[186:189], v181 offset:49152
	ds_read_b128 v[190:193], v181 offset:50176
	ds_read_b128 v[194:197], v181 offset:51200
	ds_read_b128 v[198:201], v181 offset:52224
	ds_read_b128 v[202:205], v181 offset:53248
	ds_read_b128 v[224:227], v181 offset:54272
	ds_read_b128 v[228:231], v181 offset:55296
	ds_read_b128 v[232:235], v181 offset:56320
	global_load_lds_dwordx4 v[206:207], off
	s_add_i32 m0, s6, 0x2000
	s_add_u32 s0, s0, 0x40080
	v_lshl_add_u64 v[206:207], v[236:237], 0, s[56:57]
	s_addc_u32 s1, s1, 0
	s_add_i32 s6, s45, s12
	global_load_lds_dwordx4 v[206:207], off
	v_lshl_add_u64 v[206:207], s[0:1], 0, v[0:1]
	s_mov_b32 m0, s6
	s_nop 0
	global_load_lds_dwordx4 v[206:207], off
	v_lshl_add_u64 v[206:207], s[0:1], 0, v[146:147]
	s_add_i32 m0, s6, 0x2000
	s_nop 0
	global_load_lds_dwordx4 v[206:207], off
	v_lshl_add_u64 v[206:207], v[238:239], 0, s[56:57]
	s_mov_b32 m0, s18
	s_nop 0
	global_load_lds_dwordx4 v[206:207], off
	v_lshl_add_u64 v[206:207], v[240:241], 0, s[56:57]
	s_mov_b32 m0, s19
	s_nop 0
	global_load_lds_dwordx4 v[206:207], off
	s_waitcnt vmcnt(8)
	s_waitcnt lgkmcnt(0)
	s_barrier
	s_setprio 1
	s_waitcnt lgkmcnt(0)
	v_mfma_f32_16x16x32_bf16 v[62:65], v[130:133], v[186:189], v[62:65]
	v_mfma_f32_16x16x32_bf16 v[58:61], v[138:141], v[186:189], v[58:61]
	v_mfma_f32_16x16x32_bf16 v[50:53], v[130:133], v[194:197], v[50:53]
	v_mfma_f32_16x16x32_bf16 v[42:45], v[138:141], v[194:197], v[42:45]
	v_mfma_f32_16x16x32_bf16 v[34:37], v[130:133], v[202:205], v[34:37]
	v_mfma_f32_16x16x32_bf16 v[26:29], v[138:141], v[202:205], v[26:29]
	v_mfma_f32_16x16x32_bf16 v[18:21], v[130:133], v[228:231], v[18:21]
	v_mfma_f32_16x16x32_bf16 v[10:13], v[138:141], v[228:231], v[10:13]
	v_mfma_f32_16x16x32_bf16 v[62:65], v[134:137], v[190:193], v[62:65]
	v_mfma_f32_16x16x32_bf16 v[58:61], v[142:145], v[190:193], v[58:61]
	v_mfma_f32_16x16x32_bf16 v[50:53], v[134:137], v[198:201], v[50:53]
	v_mfma_f32_16x16x32_bf16 v[42:45], v[142:145], v[198:201], v[42:45]
	v_mfma_f32_16x16x32_bf16 v[34:37], v[134:137], v[224:227], v[34:37]
	v_mfma_f32_16x16x32_bf16 v[26:29], v[142:145], v[224:227], v[26:29]
	v_mfma_f32_16x16x32_bf16 v[18:21], v[134:137], v[232:235], v[18:21]
	v_mfma_f32_16x16x32_bf16 v[10:13], v[142:145], v[232:235], v[10:13]
	s_setprio 0
	s_setprio 1
	v_mfma_f32_16x16x32_bf16 v[54:57], v[156:159], v[186:189], v[54:57]
	v_mfma_f32_16x16x32_bf16 v[46:49], v[174:177], v[186:189], v[46:49]
	v_mfma_f32_16x16x32_bf16 v[38:41], v[156:159], v[194:197], v[38:41]
	v_mfma_f32_16x16x32_bf16 v[30:33], v[174:177], v[194:197], v[30:33]
	v_mfma_f32_16x16x32_bf16 v[22:25], v[156:159], v[202:205], v[22:25]
	v_mfma_f32_16x16x32_bf16 v[14:17], v[174:177], v[202:205], v[14:17]
	v_mfma_f32_16x16x32_bf16 v[6:9], v[156:159], v[228:231], v[6:9]
	v_mfma_f32_16x16x32_bf16 v[2:5], v[174:177], v[228:231], v[2:5]
	v_mfma_f32_16x16x32_bf16 v[54:57], v[170:173], v[190:193], v[54:57]
	v_mfma_f32_16x16x32_bf16 v[46:49], v[182:185], v[190:193], v[46:49]
	v_mfma_f32_16x16x32_bf16 v[38:41], v[170:173], v[198:201], v[38:41]
	v_mfma_f32_16x16x32_bf16 v[30:33], v[182:185], v[198:201], v[30:33]
	v_mfma_f32_16x16x32_bf16 v[22:25], v[170:173], v[224:227], v[22:25]
	v_mfma_f32_16x16x32_bf16 v[14:17], v[182:185], v[224:227], v[14:17]
	v_mfma_f32_16x16x32_bf16 v[6:9], v[170:173], v[232:235], v[6:9]
	v_mfma_f32_16x16x32_bf16 v[2:5], v[182:185], v[232:235], v[2:5]
	s_setprio 0
	s_barrier
	s_add_i32 s35, s35, 2
	s_add_u32 s42, s42, 0x100
	s_addc_u32 s43, s43, 0
	s_add_u32 s29, s29, 0x100
	s_addc_u32 s34, s34, 0
	s_cmp_gt_u32 s35, 13
	s_cbranch_scc0 .LBB0_778
	s_and_b64 vcc, exec, s[36:37]
	s_cbranch_vccz .LBB0_781
	s_barrier
